# scan: static priority raise for the consumer and helper waves only (waves 0-1)
# baseline (speedup 1.0000x reference)
; #define LAS __attribute__((address_space(3)))
; __device__ __forceinline__ void scan_phase(LAS unsigned char* lds, const bf16_t* R, const bf16_t* Kb, const bf16_t* V, const bf16_t* WA, const float* k_k, const float* k_a, bf16_t* Y, int G, int bid, int tid) {
;     const int wave = __builtin_amdgcn_readfirstlane(tid >> 6), lane = tid & 63, c = lane & 15, g = lane >> 4;
;     const int wq = (wave & 1) + ((wave >> 2) << 1);
;     const int pid = wq * 64 + lane, pt = (pid >> 4) & 15, pj = pid & 15;
;     const int pid1 = tid - 256, pta = (pid1 >> 4) & 7, ptb = pta + 8;
;     const bool producer = (wave == 2) || (wave == 3) || (wave >= 6), producer1 = (wave == 4) || (wave == 5), consumer = wave < 2;
;     constexpr int NCH = T / 16;
;     for (int unit = bid; unit < 256; unit += G) {
;         const int b = unit >> 5, h = (unit >> 1) & 15, half = unit & 1;
;         const size_t rowbase = (size_t)b * T;
;         f32x4 kkw = (f32x4){0.f, 0.f, 0.f, 0.f}, kaw = kkw;
;         if (producer1) { kkw = *(const f32x4*)(k_k + h * 64 + 4 * pj); kaw = *(const f32x4*)(k_a + h * 64 + 4 * pj); }
;         u32x2 rkA = (u32x2){0u, 0u}, rrA = rkA, raA = rkA, rlA = rkA, rkB = rkA, rrB = rkA, raB = rkA, rlB = rkA; unsigned rvA = 0u, rvB = 0u;
;     ...
;         if (producer1) { CK_LOAD(A, pta, 0); CK_LOAD(B, ptb, 0); CK_P1(A, pta, 0); CK_P1(B, ptb, 0); CK_LOAD(A, pta, 1); CK_LOAD(B, ptb, 1); }
;         f32x4 H[4];
; #pragma unroll
;         for (int kt = 0; kt < 4; ++kt) H[kt] = (f32x4){0.f, 0.f, 0.f, 0.f};
;         __syncthreads();
.LBB0_873:
	v_readlane_b32 s2, v254, 1
	v_readlane_b32 s3, v254, 2
	s_cmp_lt_i32 s2, 11
	s_cselect_b64 s[2:3], -1, 0
	s_and_b64 s[4:5], s[2:3], s[0:1]
	s_andn2_b64 vcc, exec, s[4:5]
	s_cbranch_vccnz .LBB0_952
	v_readlane_b32 s98, v254, 3
	s_cmp_lt_u32 s98, 0x80
	s_cbranch_scc0 .Lmy_prio_s01
	s_setprio 1
.Lmy_prio_s01:
	v_mbcnt_lo_u32_b32 v1, -1, 0
	v_mbcnt_hi_u32_b32 v1, -1, v1
	s_lshr_b32 s98, s52, 4
	s_lshr_b32 s98, 0x63725410, s98
	s_and_b32 s98, s98, 7
	s_lshl_b32 s98, s98, 6
	s_cmpk_gt_i32 s84, 0xff
	v_add_u32_e32 v2, s98, v1
	s_mov_b64 s[0:1], s[82:83]
	v_readfirstlane_b32 s2, v2
	s_cbranch_scc1 .LBB0_952
	v_writelane_b32 v254, s4, 4
	v_and_b32_e32 v4, 63, v1
	v_and_b32_e32 v6, 15, v1
	v_writelane_b32 v254, s5, 5
	s_load_dwordx4 s[56:59], s[0:1], 0xc0
	s_load_dwordx4 s[4:7], s[0:1], 0x78
	s_load_dwordx2 s[100:101], s[0:1], 0x88
	v_writelane_b32 v254, s82, 6
	v_bfe_u32 v98, v2, 4, 3
	v_lshlrev_b32_e32 v2, 2, v2
	s_waitcnt lgkmcnt(0)
	s_add_u32 s64, s58, 0x16000000
	s_addc_u32 s65, s59, 0
	s_add_u32 s66, s56, 0x4000000
	s_addc_u32 s67, s57, 0
	s_add_u32 s68, s58, 0x8000000
	s_addc_u32 s69, s59, 0
	s_ashr_i32 s10, s2, 6
	s_and_b32 s3, s2, 0xffffff80
	s_cmpk_eq_i32 s3, 0x80
	s_cselect_b64 s[0:1], -1, 0
	s_cmp_gt_i32 s10, 5
	s_cselect_b64 s[8:9], -1, 0
	s_or_b64 s[70:71], s[0:1], s[8:9]
	s_cmpk_eq_i32 s3, 0x100
	s_cselect_b64 s[72:73], -1, 0
	s_cmpk_lg_i32 s3, 0x100
	v_writelane_b32 v254, s83, 7
	s_cselect_b64 s[0:1], -1, 0
	s_cmp_lt_i32 s10, 2
	v_writelane_b32 v254, s0, 8
	s_cselect_b64 s[76:77], -1, 0
	s_ashr_i32 s8, s2, 7
	v_writelane_b32 v254, s1, 9
	s_and_b32 s0, s10, 1
	s_and_b32 s1, s8, -2
	s_or_b32 s30, s0, s1
	s_mul_i32 s0, s10, 0xa00
	v_lshl_or_b32 v0, s30, 6, v4
	s_add_i32 s33, s0, 0
	s_lshl_b32 s0, s10, 4
	v_bfe_u32 v5, v0, 4, 4
	v_mov_b32_e32 v0, 0
	s_lshl_b32 s31, s30, 2
	s_ashr_i32 s1, s0, 31
	v_and_b32_e32 v103, 0x1fc, v2
	v_lshlrev_b32_e32 v2, 3, v6
	v_mov_b32_e32 v3, v0
	s_cmp_gt_i32 s8, -1
	v_lshl_add_u64 v[112:113], s[56:57], 0, v[2:3]
	v_lshl_add_u64 v[114:115], s[64:65], 0, v[2:3]
	v_lshlrev_b32_e32 v3, 4, v1
	s_cselect_b64 s[8:9], -1, 0
	s_cmp_lg_u32 s30, 0
	v_bfe_u32 v7, v1, 4, 2
	v_lshlrev_b32_e32 v102, 2, v6
	v_and_b32_e32 v165, 48, v3
	v_lshlrev_b32_e32 v3, 1, v1
	s_cselect_b64 s[82:83], -1, 0
	s_cmp_gt_i32 s30, 0
	v_and_b32_e32 v166, 8, v3
	v_or_b32_e32 v3, v102, v7
	s_mov_b32 s75, s84
	s_cselect_b64 s[84:85], -1, 0
	s_cmp_lt_u32 s31, 5
	v_mul_u32_u24_e32 v3, 40, v3
	s_cselect_b64 s[86:87], -1, 0
	s_cmp_gt_i32 s30, 1
	v_lshlrev_b32_e32 v104, 4, v6
	v_mov_b32_e32 v105, v0
	v_lshl_add_u32 v167, s30, 3, v3
	v_and_b32_e32 v171, 48, v1
	v_lshlrev_b32_e32 v3, 2, v7
	v_and_b32_e32 v1, 16, v1
	s_cselect_b64 s[88:89], -1, 0
	s_cmp_lt_u32 s31, 9
	v_lshl_add_u64 v[108:109], s[4:5], 0, v[104:105]
	v_lshl_add_u64 v[206:207], s[100:101], 0, v[104:105]
	v_cmp_eq_u32_e64 s[4:5], 0, v1
	s_cselect_b64 s[90:91], -1, 0
	s_cmp_gt_i32 s30, 2
	v_or_b32_e32 v1, 1, v3
	v_or_b32_e32 v100, 8, v98
	s_cselect_b64 s[92:93], -1, 0
	s_cmp_lt_u32 s31, 13
	v_cmp_lt_u32_e32 vcc, v1, v6
	v_or_b32_e32 v1, 2, v3
	v_lshlrev_b32_e32 v155, 6, v100
	v_lshlrev_b32_e32 v161, 8, v5
	s_cselect_b64 s[94:95], -1, 0
	v_cmp_lt_u32_e64 s[48:49], v1, v6
	v_cmp_gt_u32_e64 s[42:43], v1, v6
	v_or_b32_e32 v1, 3, v3
	s_add_i32 s51, 0, 0x13400
	v_cmp_lt_u32_e64 s[44:45], v1, v6
	v_cmp_gt_u32_e64 s[46:47], v1, v6
	v_add_u32_e32 v1, s51, v155
	v_add_u32_e32 v178, 0, v161
	s_movk_i32 s51, 0xff40
	s_movk_i32 s50, 0x50
	v_writelane_b32 v254, s8, 10
	v_mad_i32_i24 v179, v5, s51, v178
	v_lshl_add_u64 v[106:107], s[6:7], 0, v[104:105]
	v_lshlrev_b32_e32 v162, 6, v5
	v_mul_u32_u24_e32 v163, 0x90, v5
	v_lshlrev_b32_e32 v169, 1, v5
	v_cmp_eq_u32_e64 s[2:3], 15, v5
	v_cmp_gt_u32_e64 s[6:7], 32, v4
	v_writelane_b32 v254, s9, 11
	v_cmp_eq_u32_e64 s[8:9], 0, v5
	v_cmp_gt_u32_e64 s[10:11], 2, v5
	v_cmp_gt_u32_e64 s[12:13], 3, v5
	v_cmp_gt_u32_e64 s[14:15], 4, v5
	v_cmp_lt_u32_e64 s[16:17], 4, v5
	v_cmp_gt_u32_e64 s[18:19], 6, v5
	v_cmp_gt_u32_e64 s[20:21], 7, v5
	v_cmp_gt_u32_e64 s[22:23], 8, v5
	v_cmp_lt_u32_e64 s[24:25], 8, v5
	v_cmp_gt_u32_e64 s[26:27], 10, v5
	v_cmp_gt_u32_e64 s[28:29], 11, v5
	v_cmp_gt_u32_e64 s[30:31], 12, v5
	v_cmp_lt_u32_e64 s[34:35], 12, v5
	v_cmp_gt_u32_e64 s[36:37], 14, v5
	v_cmp_lt_u32_e64 s[38:39], v3, v6
	v_cmp_gt_u32_e64 s[40:41], v3, v6
	v_mad_u32_u24 v3, v5, s50, v179
	v_lshlrev_b32_e32 v4, 13, v7
	v_mov_b32_e32 v5, v0
	v_lshlrev_b32_e32 v110, 1, v6
	v_lshl_add_u64 v[4:5], s[0:1], 1, v[4:5]
	v_or_b32_e32 v4, v4, v110
	v_lshlrev_b32_e32 v9, 8, v7
	v_lshl_add_u64 v[116:117], s[58:59], 0, v[4:5]
	v_lshl_or_b32 v4, v98, 12, v2
	v_mov_b32_e32 v5, v0
	v_and_b32_e32 v164, 64, v2
	v_add3_u32 v172, s33, v9, v102
	v_or_b32_e32 v9, s0, v6
	v_lshl_add_u64 v[4:5], s[58:59], 0, v[4:5]
	s_mov_b64 s[0:1], 0x8038800
	v_mul_lo_u32 v173, v9, 40
	v_add3_u32 v9, v3, v164, v165
	v_lshlrev_b32_e32 v3, 6, v6
	v_lshl_add_u64 v[118:119], v[4:5], 0, s[0:1]
	v_lshlrev_b32_e32 v4, 11, v98
	v_lshl_or_b32 v99, v98, 8, v104
	v_lshl_or_b32 v105, v100, 8, v104
	v_mul_u32_u24_e32 v168, 0x50, v6
	v_mul_u32_u24_e32 v170, 0x90, v6
	v_mul_u32_u24_e32 v175, 40, v6
	v_mad_u32_u24 v180, v6, s50, 0
	v_sub_u32_e32 v6, 0, v3
	v_or_b32_e32 v2, v4, v2
	v_mov_b32_e32 v3, v0
	v_add_u32_e32 v101, 0, v99
	v_add_u32_e32 v111, 0, v105
	v_add_u32_e32 v8, 0, v155
	v_lshl_add_u64 v[120:121], s[56:57], 0, v[2:3]
	v_lshl_add_u64 v[122:123], s[58:59], 0, v[2:3]
	v_or_b32_e32 v2, v4, v102
	s_or_b64 s[48:49], s[44:45], s[48:49]
	s_mov_b32 s79, 0
	v_add_u32_e32 v160, 0, v104
	v_lshlrev_b32_e32 v174, 3, v7
	v_add_u32_e32 v176, 0xf400, v101
	v_add_u32_e32 v177, 0xf400, v111
	v_lshl_add_u64 v[124:125], s[56:57], 0, v[2:3]
	s_mov_b32 s74, 0x179abe15
	v_add_u32_e32 v181, v9, v166
	v_add_u32_e32 v181, 0x14000, v181
	v_add_u32_e32 v182, v180, v6
	v_add_u32_e32 v182, 0x14000, v182
	s_xor_b64 s[58:59], s[70:71], -1
	v_mov_b32_e32 v183, 0x5368d4a5
	v_add_u32_e32 v184, v8, v102
	v_add_u32_e32 v185, v1, v102
	s_or_b64 s[50:51], s[48:49], vcc
	v_writelane_b32 v254, s75, 12
	s_branch .LBB0_877

; __device__ __forceinline__ unsigned xb_ld(unsigned* p)              { return __hip_atomic_load(p, __ATOMIC_RELAXED, __HIP_MEMORY_SCOPE_AGENT); }
; __device__ __forceinline__ unsigned xb_add(unsigned* p, unsigned v) { return __hip_atomic_fetch_add(p, v, __ATOMIC_RELAXED, __HIP_MEMORY_SCOPE_AGENT); }
; __device__ __forceinline__ void xcd_barrier_complete(unsigned* bar, unsigned x, unsigned& nloc, unsigned& nx) {
;     const unsigned G = gridDim.x * gridDim.y * gridDim.z;
;     unsigned sum, cnt, mine, sp = 0u;
;     for (;;) {
;         sum = 0u; cnt = 0u; mine = 0u;
; #pragma unroll
;         for (unsigned j = 0; j < 16; ++j) { const unsigned c = xb_ld(&bar[XB_XCNT(j)]); sum += c; cnt += (c > 0u) ? 1u : 0u; mine = (j == x) ? c : mine; }
; __device__ __forceinline__ void xcd_barrier(const XcdBarrier& b, const int tid_) {
;     asm volatile("s_waitcnt vmcnt(0)" ::: "memory");
;     __syncthreads();
;     if (tid_ == 0) {
;         unsigned* bar = b.bar;
;         __builtin_amdgcn_s_waitcnt(0);
;         unsigned nloc = b.st[0], nx = b.st[1];
;         if (nloc == 0u) { xcd_barrier_complete(bar, b.x, nloc, nx); b.st[0] = nloc; b.st[1] = nx; }
;         const unsigned old = xb_add(&bar[XB_XSUB(b.x)], 1u);
.LBB0_952:
	s_setprio 0
	v_readlane_b32 s0, v254, 1
	v_readlane_b32 s1, v254, 2
	s_cmp_gt_i32 s1, 11
	s_cselect_b64 s[0:1], -1, 0
	s_and_b64 s[2:3], s[4:5], s[0:1]
	s_andn2_b64 vcc, exec, s[2:3]
	s_cbranch_vccnz .LBB0_1006
	s_mov_b64 s[4:5], s[82:83]
	v_mbcnt_lo_u32_b32 v0, -1, 0
	v_mbcnt_hi_u32_b32 v0, -1, v0
	s_getreg_b32 s6, hwreg(HW_REG_XCC_ID, 0, 4)
	s_waitcnt vmcnt(0)
	v_sub_u32_e32 v0, 0, v0
	v_cmp_eq_u32_e32 vcc, s52, v0
	s_waitcnt vmcnt(0)
	s_barrier
	s_and_saveexec_b64 s[2:3], vcc
	s_cbranch_execz .LBB0_1005
	s_add_i32 s7, 0, 0x23fc0
	v_mov_b32_e32 v0, s7
	s_load_dwordx2 s[4:5], s[4:5], 0xc8
	s_waitcnt vmcnt(0) expcnt(0) lgkmcnt(0)
	ds_read_b32 v2, v0
	s_add_i32 s7, 0, 0x23fc4
	v_mov_b32_e32 v0, s7
	ds_read_b32 v0, v0
	s_and_b32 s33, s6, 15
	s_waitcnt lgkmcnt(1)
	v_cmp_ne_u32_e32 vcc, 0, v2
	s_cbranch_vccnz .LBB0_969
	v_readlane_b32 s6, v254, 0
	s_mul_i32 s48, s55, s6
	s_add_u32 s6, s4, 0x1900200
	s_addc_u32 s7, s5, 0
	s_add_u32 s8, s4, 0x1900400
	s_addc_u32 s9, s5, 0
	s_add_u32 s10, s4, 0x1900500
	s_addc_u32 s11, s5, 0
	s_add_u32 s12, s4, 0x1900600
	s_addc_u32 s13, s5, 0
	s_add_u32 s14, s4, 0x1900700
	s_addc_u32 s15, s5, 0
	s_add_u32 s16, s4, 0x1900800
	s_addc_u32 s17, s5, 0
	s_add_u32 s18, s4, 0x1900900
	s_addc_u32 s19, s5, 0
	s_add_u32 s20, s4, 0x1900a00
	s_addc_u32 s21, s5, 0
	s_add_u32 s22, s4, 0x1900b00
	s_addc_u32 s23, s5, 0
	s_add_u32 s24, s4, 0x1900c00
	s_addc_u32 s25, s5, 0
	s_add_u32 s26, s4, 0x1900d00
	s_addc_u32 s27, s5, 0
	s_add_u32 s28, s4, 0x1900e00
	s_addc_u32 s29, s5, 0
	s_add_u32 s30, s4, 0x1900f00
	s_addc_u32 s31, s5, 0
	s_add_u32 s34, s4, 0x1901000
	s_addc_u32 s35, s5, 0
	s_add_u32 s36, s4, 0x1901100
	s_addc_u32 s37, s5, 0
	s_add_u32 s38, s4, 0x1901200
	s_addc_u32 s39, s5, 0
	s_add_u32 s40, s4, 0x1901300
	s_mul_i32 s48, s48, s54
	s_addc_u32 s41, s5, 0
	s_mov_b32 s49, 1
	v_mov_b32_e32 v16, 0
	s_branch .LBB0_957
